# attention loop barrier: plain full drain instead of the counted per-role waits (loads are a half ahead anyway)
# baseline (speedup 1.0000x reference)
; #define SBAR() __builtin_amdgcn_sched_barrier(0)
; #define WAIT_BAR(N) asm volatile("s_waitcnt vmcnt(" #N ") lgkmcnt(0)\n\ts_barrier" ::: "memory")
; #define DMA_TILE(t, ks, vs) do { glds16(ksrc + (long)(t) * KVBLK * KNP, (unsigned)__builtin_amdgcn_readfirstlane(kdst + (ks) * KSLOT)); \
;         glds16(k2src + (long)(t) * KVBLK * KPP, (unsigned)__builtin_amdgcn_readfirstlane(k2dst + (ks) * KSLOT)); \
;         glds16(vsrc + (long)(t) * KVBLK * VP, (unsigned)__builtin_amdgcn_readfirstlane(vdst + (vs) * VSLOT)); } while (0)
; #define K_LOAD(ks) do { const LAS char* kp_ = kp0 + (ks) * KSLOT; \
;         _Pragma("unroll") for (int i_ = 0; i_ < 6; ++i_) { kf[2 * i_] = *(const LAS bf16x8*)(kp_ + i_ * 2048); kf[2 * i_ + 1] = *(const LAS bf16x8*)(kp_ + i_ * 2048 + 512); } SBAR(); } while (0)
; #define V_LOAD(vs) do { const LAS char* vp_ = vp0 + (vs) * VSLOT; \
;         _Pragma("unroll") for (int i_ = 0; i_ < 8; ++i_) { vlo[i_] = vtr(vp_ + ((i_ >> 2) * 4096 + (i_ & 3) * 1024)); vhi[i_] = vtr(vp_ + ((i_ >> 2) * 4096 + (i_ & 3) * 1024 + 512)); } SBAR(); } while (0)
; __device__ __forceinline__ void attn_unit(int b, int h, int qb, const bf16* Q, const bf16* __restrict__ Kn, const bf16* __restrict__ Kpe, const bf16* __restrict__ V, bf16* O, float* ASS, LAS char* shm) {
;     ...
;         for (int t = 0; t < NT; ++t) {
;             if (t + 1 < NT) { WAIT_BAR(3); } else { WAIT_BAR(0); }
;             K_LOAD(ks);
;             if (t + 2 < NT) DMA_TILE(t + 2, (ks == 0) ? 2 : ks - 1, (vs + 2) & 3);
;             SBAR();
;             QK_MMA(t);
;             V_LOAD(vs);
;             SOFTMAX();
;             PV_MMA();
;             ks = (ks == 2) ? 0 : ks + 1; vs = (vs + 1) & 3;
;         }
.Lat_u1_loop:
	s_waitcnt vmcnt(0) lgkmcnt(0)
	s_barrier
	s_lshr_b32 s4, s69, 1
	s_sub_u32 s4, s52, s4
	s_cmp_gt_i32 s4, s87
	s_cbranch_scc1 .Lat_u1x_noqk
	s_mul_i32 s53, s48, 0x3000
	v_add_u32_e32 v158, s53, v146
	ds_read_b128 v[196:199], v158
	ds_read_b128 v[200:203], v158 offset:512
	ds_read_b128 v[204:207], v158 offset:2048
	ds_read_b128 v[208:211], v158 offset:2560
	ds_read_b128 v[212:215], v158 offset:4096
	ds_read_b128 v[230:233], v158 offset:4608
	ds_read_b128 v[234:237], v158 offset:6144
	ds_read_b128 v[164:167], v158 offset:6656
	ds_read_b128 v[168:171], v158 offset:8192
	ds_read_b128 v[172:175], v158 offset:8704
	ds_read_b128 v[148:151], v158 offset:10240
	ds_read_b128 v[152:155], v158 offset:10752
	s_lshl_b32 s4, s50, 13
	s_add_i32 s4, s4, 0x6000
	s_and_b32 s4, s4, 0x6000
	v_add_u32_e32 v159, s4, v144
	v_mov_b32_e32 v156, 0
	v_mov_b32_e32 v157, 0
	s_waitcnt lgkmcnt(11)
	v_mfma_f32_32x32x16_bf16 v[238:253], v[196:199], v[100:103], v[104:119]
	ds_read_b64_tr_b16 v[196:197], v159 offset:36864
	ds_read_b64_tr_b16 v[198:199], v159 offset:37376
	v_exp_f32_e32 v64, v64
	v_exp_f32_e32 v65, v65
	v_add_f32_e32 v156, v156, v64
	v_add_f32_e32 v156, v156, v65
	v_cvt_pk_bf16_f32 v64, v64, v65
	s_waitcnt lgkmcnt(12)
	v_mfma_f32_32x32x16_bf16 v[180:195], v[200:203], v[100:103], v[104:119]
	ds_read_b64_tr_b16 v[200:201], v159 offset:37888
	ds_read_b64_tr_b16 v[202:203], v159 offset:38400
	v_exp_f32_e32 v66, v66
	v_exp_f32_e32 v67, v67
	v_add_f32_e32 v157, v157, v66
	v_add_f32_e32 v157, v157, v67
	v_cvt_pk_bf16_f32 v65, v66, v67
	s_waitcnt lgkmcnt(13)
	v_mfma_f32_32x32x16_bf16 v[238:253], v[204:207], v[96:99], v[238:253]
	ds_read_b64_tr_b16 v[204:205], v159 offset:38912
	ds_read_b64_tr_b16 v[206:207], v159 offset:39424
	v_exp_f32_e32 v68, v68
	v_exp_f32_e32 v69, v69
	v_add_f32_e32 v156, v156, v68
	v_add_f32_e32 v156, v156, v69
	v_cvt_pk_bf16_f32 v66, v68, v69
	s_waitcnt lgkmcnt(14)
	v_mfma_f32_32x32x16_bf16 v[180:195], v[208:211], v[96:99], v[180:195]
	ds_read_b64_tr_b16 v[208:209], v159 offset:39936
	ds_read_b64_tr_b16 v[210:211], v159 offset:40448
	v_exp_f32_e32 v70, v70
	v_exp_f32_e32 v71, v71
	v_add_f32_e32 v157, v157, v70
	v_add_f32_e32 v157, v157, v71
	v_cvt_pk_bf16_f32 v67, v70, v71
	s_waitcnt lgkmcnt(15)
	v_mfma_f32_32x32x16_bf16 v[238:253], v[212:215], v[92:95], v[238:253]
	ds_read_b64_tr_b16 v[212:213], v159 offset:40960
	ds_read_b64_tr_b16 v[214:215], v159 offset:41472
	v_exp_f32_e32 v72, v72
	v_exp_f32_e32 v73, v73
	v_add_f32_e32 v156, v156, v72
	v_add_f32_e32 v156, v156, v73
	v_cvt_pk_bf16_f32 v68, v72, v73
	s_waitcnt lgkmcnt(15)
	v_mfma_f32_32x32x16_bf16 v[180:195], v[230:233], v[92:95], v[180:195]
	ds_read_b64_tr_b16 v[230:231], v159 offset:41984
	ds_read_b64_tr_b16 v[232:233], v159 offset:42496
	v_exp_f32_e32 v74, v74
	v_exp_f32_e32 v75, v75
	v_add_f32_e32 v157, v157, v74
	v_add_f32_e32 v157, v157, v75
	v_cvt_pk_bf16_f32 v69, v74, v75
	s_waitcnt lgkmcnt(15)
	v_mfma_f32_32x32x16_bf16 v[238:253], v[234:237], v[88:91], v[238:253]
	ds_read_b64_tr_b16 v[234:235], v159 offset:43008
	ds_read_b64_tr_b16 v[236:237], v159 offset:43520
	v_exp_f32_e32 v76, v76
	v_exp_f32_e32 v77, v77
	v_add_f32_e32 v156, v156, v76
	v_add_f32_e32 v156, v156, v77
	v_cvt_pk_bf16_f32 v70, v76, v77
	s_waitcnt lgkmcnt(15)
	v_mfma_f32_32x32x16_bf16 v[180:195], v[164:167], v[88:91], v[180:195]
	ds_read_b64_tr_b16 v[164:165], v159 offset:44032
	ds_read_b64_tr_b16 v[166:167], v159 offset:44544
	v_exp_f32_e32 v78, v78
	v_exp_f32_e32 v79, v79
	v_add_f32_e32 v157, v157, v78
	v_add_f32_e32 v157, v157, v79
	v_cvt_pk_bf16_f32 v71, v78, v79
	s_waitcnt lgkmcnt(15)
	v_mfma_f32_32x32x16_bf16 v[238:253], v[168:171], v[84:87], v[238:253]
	v_exp_f32_e32 v48, v48
	v_exp_f32_e32 v49, v49
	v_add_f32_e32 v156, v156, v48
	v_add_f32_e32 v156, v156, v49
	v_cvt_pk_bf16_f32 v48, v48, v49
	s_waitcnt lgkmcnt(15)
	v_mfma_f32_32x32x16_bf16 v[180:195], v[172:175], v[84:87], v[180:195]
	v_exp_f32_e32 v50, v50
	v_exp_f32_e32 v51, v51
	v_add_f32_e32 v157, v157, v50
	v_add_f32_e32 v157, v157, v51
	v_cvt_pk_bf16_f32 v49, v50, v51
	s_waitcnt lgkmcnt(15)
	v_mfma_f32_32x32x16_bf16 v[238:253], v[148:151], v[80:83], v[238:253]
	v_exp_f32_e32 v52, v52
	v_exp_f32_e32 v53, v53
	v_add_f32_e32 v156, v156, v52
	v_add_f32_e32 v156, v156, v53
	v_cvt_pk_bf16_f32 v50, v52, v53
	s_waitcnt lgkmcnt(15)
	v_mfma_f32_32x32x16_bf16 v[180:195], v[152:155], v[80:83], v[180:195]
	v_exp_f32_e32 v54, v54
	v_exp_f32_e32 v55, v55
	v_add_f32_e32 v157, v157, v54
	v_add_f32_e32 v157, v157, v55
	v_cvt_pk_bf16_f32 v51, v54, v55
	s_nop 1
	s_waitcnt lgkmcnt(0)
	v_mfma_f32_32x32x16_bf16 v[16:31], v[196:199], v[64:67], v[16:31]
	v_exp_f32_e32 v56, v56
	v_exp_f32_e32 v57, v57
	v_add_f32_e32 v156, v156, v56
	v_add_f32_e32 v156, v156, v57
	v_cvt_pk_bf16_f32 v52, v56, v57
	s_nop 1
	v_mfma_f32_32x32x16_bf16 v[32:47], v[212:215], v[64:67], v[32:47]
	s_mul_i32 s53, s48, 0x3000
	s_add_i32 s4, s52, 2
	s_cmp_ge_u32 s4, s86
	s_cbranch_scc1 .Lat_u1x_nodma
	s_add_i32 s4, s53, 0xffffd000
	s_cmp_lg_u32 s48, 0
	s_cselect_b32 s4, s4, 0x6000
	s_add_i32 s5, s4, s97
	s_mov_b32 m0, s5
	s_add_i32 s4, s4, s72
	global_load_lds_dwordx4 v[126:127], off
	s_mov_b32 m0, s4
	s_cmp_lt_u32 s69, 4
	s_cbranch_scc0 .Lat_u1x_nok2
	global_load_lds_dwordx4 v[14:15], off

; #define SBAR() __builtin_amdgcn_sched_barrier(0)
; #define WAIT_BAR(N) asm volatile("s_waitcnt vmcnt(" #N ") lgkmcnt(0)\n\ts_barrier" ::: "memory")
; #define DMA_TILE(t, ks, vs) do { glds16(ksrc + (long)(t) * KVBLK * KNP, (unsigned)__builtin_amdgcn_readfirstlane(kdst + (ks) * KSLOT)); \
;         glds16(k2src + (long)(t) * KVBLK * KPP, (unsigned)__builtin_amdgcn_readfirstlane(k2dst + (ks) * KSLOT)); \
;         glds16(vsrc + (long)(t) * KVBLK * VP, (unsigned)__builtin_amdgcn_readfirstlane(vdst + (vs) * VSLOT)); } while (0)
; #define K_LOAD(ks) do { const LAS char* kp_ = kp0 + (ks) * KSLOT; \
;         _Pragma("unroll") for (int i_ = 0; i_ < 6; ++i_) { kf[2 * i_] = *(const LAS bf16x8*)(kp_ + i_ * 2048); kf[2 * i_ + 1] = *(const LAS bf16x8*)(kp_ + i_ * 2048 + 512); } SBAR(); } while (0)
; #define V_LOAD(vs) do { const LAS char* vp_ = vp0 + (vs) * VSLOT; \
;         _Pragma("unroll") for (int i_ = 0; i_ < 8; ++i_) { vlo[i_] = vtr(vp_ + ((i_ >> 2) * 4096 + (i_ & 3) * 1024)); vhi[i_] = vtr(vp_ + ((i_ >> 2) * 4096 + (i_ & 3) * 1024 + 512)); } SBAR(); } while (0)
; __device__ __forceinline__ void attn_unit(int b, int h, int qb, const bf16* Q, const bf16* __restrict__ Kn, const bf16* __restrict__ Kpe, const bf16* __restrict__ V, bf16* O, float* ASS, LAS char* shm) {
;     ...
;         for (int t = 0; t < NT; ++t) {
;             if (t + 1 < NT) { WAIT_BAR(3); } else { WAIT_BAR(0); }
;             K_LOAD(ks);
;             if (t + 2 < NT) DMA_TILE(t + 2, (ks == 0) ? 2 : ks - 1, (vs + 2) & 3);
;             SBAR();
;             QK_MMA(t);
;             V_LOAD(vs);
;             SOFTMAX();
;             PV_MMA();
;             ks = (ks == 2) ? 0 : ks + 1; vs = (vs + 1) & 3;
;         }
.Lat_u1x_end:
	s_cmp_eq_u32 s52, s86
	s_cbranch_scc1 .Lat_u1_tail
	s_waitcnt vmcnt(0) lgkmcnt(0)
	s_barrier
	s_lshr_b32 s4, s69, 1
	s_sub_u32 s4, s52, s4
	s_cmp_gt_i32 s4, s87
	s_cbranch_scc1 .Lat_u1y_noqk
	s_mul_i32 s53, s48, 0x3000
	v_add_u32_e32 v158, s53, v146
	ds_read_b128 v[196:199], v158
	ds_read_b128 v[200:203], v158 offset:512
	ds_read_b128 v[204:207], v158 offset:2048
	ds_read_b128 v[208:211], v158 offset:2560
	ds_read_b128 v[212:215], v158 offset:4096
	ds_read_b128 v[230:233], v158 offset:4608
	ds_read_b128 v[234:237], v158 offset:6144
	ds_read_b128 v[164:167], v158 offset:6656
	ds_read_b128 v[168:171], v158 offset:8192
	ds_read_b128 v[172:175], v158 offset:8704
	ds_read_b128 v[148:151], v158 offset:10240
	ds_read_b128 v[152:155], v158 offset:10752
	s_lshl_b32 s4, s50, 13
	s_add_i32 s4, s4, 0x6000
	s_and_b32 s4, s4, 0x6000
	v_add_u32_e32 v159, s4, v144
	v_mov_b32_e32 v156, 0
	v_mov_b32_e32 v157, 0
	s_waitcnt lgkmcnt(11)
	v_mfma_f32_32x32x16_bf16 v[64:79], v[196:199], v[100:103], v[104:119]
	ds_read_b64_tr_b16 v[196:197], v159 offset:36864
	ds_read_b64_tr_b16 v[198:199], v159 offset:37376
	v_exp_f32_e32 v238, v238
	v_exp_f32_e32 v239, v239
	v_add_f32_e32 v156, v156, v238
	v_add_f32_e32 v156, v156, v239
	v_cvt_pk_bf16_f32 v238, v238, v239
	s_waitcnt lgkmcnt(12)
	v_mfma_f32_32x32x16_bf16 v[48:63], v[200:203], v[100:103], v[104:119]
	ds_read_b64_tr_b16 v[200:201], v159 offset:37888
	ds_read_b64_tr_b16 v[202:203], v159 offset:38400
	v_exp_f32_e32 v240, v240
	v_exp_f32_e32 v241, v241
	v_add_f32_e32 v157, v157, v240
	v_add_f32_e32 v157, v157, v241
	v_cvt_pk_bf16_f32 v239, v240, v241
	s_waitcnt lgkmcnt(13)
	v_mfma_f32_32x32x16_bf16 v[64:79], v[204:207], v[96:99], v[64:79]
	ds_read_b64_tr_b16 v[204:205], v159 offset:38912
	ds_read_b64_tr_b16 v[206:207], v159 offset:39424
	v_exp_f32_e32 v242, v242
	v_exp_f32_e32 v243, v243
	v_add_f32_e32 v156, v156, v242
	v_add_f32_e32 v156, v156, v243
	v_cvt_pk_bf16_f32 v240, v242, v243
	s_waitcnt lgkmcnt(14)
	v_mfma_f32_32x32x16_bf16 v[48:63], v[208:211], v[96:99], v[48:63]
	ds_read_b64_tr_b16 v[208:209], v159 offset:39936
	ds_read_b64_tr_b16 v[210:211], v159 offset:40448
	v_exp_f32_e32 v244, v244
	v_exp_f32_e32 v245, v245
	v_add_f32_e32 v157, v157, v244
	v_add_f32_e32 v157, v157, v245
	v_cvt_pk_bf16_f32 v241, v244, v245
	s_waitcnt lgkmcnt(15)
	v_mfma_f32_32x32x16_bf16 v[64:79], v[212:215], v[92:95], v[64:79]
	ds_read_b64_tr_b16 v[212:213], v159 offset:40960
	ds_read_b64_tr_b16 v[214:215], v159 offset:41472
	v_exp_f32_e32 v246, v246
	v_exp_f32_e32 v247, v247
	v_add_f32_e32 v156, v156, v246
	v_add_f32_e32 v156, v156, v247
	v_cvt_pk_bf16_f32 v242, v246, v247
	s_waitcnt lgkmcnt(15)
	v_mfma_f32_32x32x16_bf16 v[48:63], v[230:233], v[92:95], v[48:63]
	ds_read_b64_tr_b16 v[230:231], v159 offset:41984
	ds_read_b64_tr_b16 v[232:233], v159 offset:42496
	v_exp_f32_e32 v248, v248
	v_exp_f32_e32 v249, v249
	v_add_f32_e32 v157, v157, v248
	v_add_f32_e32 v157, v157, v249
	v_cvt_pk_bf16_f32 v243, v248, v249
	s_waitcnt lgkmcnt(15)
	v_mfma_f32_32x32x16_bf16 v[64:79], v[234:237], v[88:91], v[64:79]
	ds_read_b64_tr_b16 v[234:235], v159 offset:43008
	ds_read_b64_tr_b16 v[236:237], v159 offset:43520
	v_exp_f32_e32 v250, v250
	v_exp_f32_e32 v251, v251
	v_add_f32_e32 v156, v156, v250
	v_add_f32_e32 v156, v156, v251
	v_cvt_pk_bf16_f32 v244, v250, v251
	s_waitcnt lgkmcnt(15)
	v_mfma_f32_32x32x16_bf16 v[48:63], v[164:167], v[88:91], v[48:63]
	ds_read_b64_tr_b16 v[164:165], v159 offset:44032
	ds_read_b64_tr_b16 v[166:167], v159 offset:44544
	v_exp_f32_e32 v252, v252
	v_exp_f32_e32 v253, v253
	v_add_f32_e32 v157, v157, v252
	v_add_f32_e32 v157, v157, v253
	v_cvt_pk_bf16_f32 v245, v252, v253
	s_waitcnt lgkmcnt(15)
	v_mfma_f32_32x32x16_bf16 v[64:79], v[168:171], v[84:87], v[64:79]
	v_exp_f32_e32 v180, v180
	v_exp_f32_e32 v181, v181
	v_add_f32_e32 v156, v156, v180
	v_add_f32_e32 v156, v156, v181
	v_cvt_pk_bf16_f32 v180, v180, v181
	s_waitcnt lgkmcnt(15)
	v_mfma_f32_32x32x16_bf16 v[48:63], v[172:175], v[84:87], v[48:63]
	v_exp_f32_e32 v182, v182
	v_exp_f32_e32 v183, v183
	v_add_f32_e32 v157, v157, v182
	v_add_f32_e32 v157, v157, v183
	v_cvt_pk_bf16_f32 v181, v182, v183
	s_waitcnt lgkmcnt(15)
	v_mfma_f32_32x32x16_bf16 v[64:79], v[148:151], v[80:83], v[64:79]
	v_exp_f32_e32 v184, v184
	v_exp_f32_e32 v185, v185
	v_add_f32_e32 v156, v156, v184
	v_add_f32_e32 v156, v156, v185
	v_cvt_pk_bf16_f32 v182, v184, v185
	s_waitcnt lgkmcnt(15)
	v_mfma_f32_32x32x16_bf16 v[48:63], v[152:155], v[80:83], v[48:63]
	v_exp_f32_e32 v186, v186
	v_exp_f32_e32 v187, v187
	v_add_f32_e32 v157, v157, v186
	v_add_f32_e32 v157, v157, v187
	v_cvt_pk_bf16_f32 v183, v186, v187
	s_nop 1
	s_waitcnt lgkmcnt(0)
	v_mfma_f32_32x32x16_bf16 v[16:31], v[196:199], v[238:241], v[16:31]
	v_exp_f32_e32 v188, v188
	v_exp_f32_e32 v189, v189
	v_add_f32_e32 v156, v156, v188
	v_add_f32_e32 v156, v156, v189
	v_cvt_pk_bf16_f32 v184, v188, v189
	s_nop 1
	v_mfma_f32_32x32x16_bf16 v[32:47], v[212:215], v[238:241], v[32:47]
	s_mul_i32 s53, s48, 0x3000
	s_add_i32 s4, s52, 2
	s_cmp_ge_u32 s4, s86
	s_cbranch_scc1 .Lat_u1y_nodma
	s_add_i32 s4, s53, 0xffffd000
	s_cmp_lg_u32 s48, 0
	s_cselect_b32 s4, s4, 0x6000
	s_add_i32 s5, s4, s97
	s_mov_b32 m0, s5
	s_add_i32 s4, s4, s72
	global_load_lds_dwordx4 v[126:127], off
	s_mov_b32 m0, s4
	s_cmp_lt_u32 s69, 4
	s_cbranch_scc0 .Lat_u1y_nok2
	global_load_lds_dwordx4 v[14:15], off

; #define SBAR() __builtin_amdgcn_sched_barrier(0)
; #define WAIT_BAR(N) asm volatile("s_waitcnt vmcnt(" #N ") lgkmcnt(0)\n\ts_barrier" ::: "memory")
; #define DMA_TILE(t, ks, vs) do { glds16(ksrc + (long)(t) * KVBLK * KNP, (unsigned)__builtin_amdgcn_readfirstlane(kdst + (ks) * KSLOT)); \
;         glds16(k2src + (long)(t) * KVBLK * KPP, (unsigned)__builtin_amdgcn_readfirstlane(k2dst + (ks) * KSLOT)); \
;         glds16(vsrc + (long)(t) * KVBLK * VP, (unsigned)__builtin_amdgcn_readfirstlane(vdst + (vs) * VSLOT)); } while (0)
; #define K_LOAD(ks) do { const LAS char* kp_ = kp0 + (ks) * KSLOT; \
;         _Pragma("unroll") for (int i_ = 0; i_ < 6; ++i_) { kf[2 * i_] = *(const LAS bf16x8*)(kp_ + i_ * 2048); kf[2 * i_ + 1] = *(const LAS bf16x8*)(kp_ + i_ * 2048 + 512); } SBAR(); } while (0)
; #define V_LOAD(vs) do { const LAS char* vp_ = vp0 + (vs) * VSLOT; \
;         _Pragma("unroll") for (int i_ = 0; i_ < 8; ++i_) { vlo[i_] = vtr(vp_ + ((i_ >> 2) * 4096 + (i_ & 3) * 1024)); vhi[i_] = vtr(vp_ + ((i_ >> 2) * 4096 + (i_ & 3) * 1024 + 512)); } SBAR(); } while (0)
; __device__ __forceinline__ void attn_unit(int b, int h, int qb, const bf16* Q, const bf16* __restrict__ Kn, const bf16* __restrict__ Kpe, const bf16* __restrict__ V, bf16* O, float* ASS, LAS char* shm) {
;     ...
;         for (int t = 0; t < NT; ++t) {
;             if (t + 1 < NT) { WAIT_BAR(3); } else { WAIT_BAR(0); }
;             if (t > 0) V_LOAD((vs + 3) & 3);
;             if (t + 2 < NT) DMA_TILE(t + 2, (ks == 0) ? 2 : ks - 1, (vs + 2) & 3);
;             SBAR();
;             if (t > 0) SOFTMAX();
;             K_LOAD(ks);
;             if (t > 0) PV_MMA();
;             QK_MMA(t);
;             ks = (ks == 2) ? 0 : ks + 1; vs = (vs + 1) & 3;
;         }
.Lat_u2_loop:
	s_waitcnt vmcnt(0) lgkmcnt(0)
	s_barrier
	s_lshr_b32 s4, s56, 1
	s_sub_u32 s4, s62, s4
	s_cmp_gt_i32 s4, s91
	s_cbranch_scc1 .Lat_u2x_noqk
	s_mul_i32 s63, s61, 0x3000
	v_add_u32_e32 v158, s63, v146
	ds_read_b128 v[196:199], v158
	ds_read_b128 v[200:203], v158 offset:512
	ds_read_b128 v[204:207], v158 offset:2048
	ds_read_b128 v[208:211], v158 offset:2560
	ds_read_b128 v[212:215], v158 offset:4096
	ds_read_b128 v[230:233], v158 offset:4608
	ds_read_b128 v[234:237], v158 offset:6144
	ds_read_b128 v[164:167], v158 offset:6656
	ds_read_b128 v[168:171], v158 offset:8192
	ds_read_b128 v[172:175], v158 offset:8704
	ds_read_b128 v[148:151], v158 offset:10240
	ds_read_b128 v[152:155], v158 offset:10752
	s_lshl_b32 s4, s64, 13
	s_add_i32 s4, s4, 0x6000
	s_and_b32 s4, s4, 0x6000
	v_add_u32_e32 v159, s4, v143
	v_mov_b32_e32 v156, 0
	v_mov_b32_e32 v157, 0
	s_waitcnt lgkmcnt(11)
	v_mfma_f32_32x32x16_bf16 v[238:253], v[196:199], v[86:89], v[104:119]
	ds_read_b64_tr_b16 v[196:197], v159 offset:36864
	ds_read_b64_tr_b16 v[198:199], v159 offset:37376
	v_exp_f32_e32 v50, v50
	v_exp_f32_e32 v51, v51
	v_add_f32_e32 v156, v156, v50
	v_add_f32_e32 v156, v156, v51
	v_cvt_pk_bf16_f32 v50, v50, v51
	s_waitcnt lgkmcnt(12)
	v_mfma_f32_32x32x16_bf16 v[180:195], v[200:203], v[86:89], v[104:119]
	ds_read_b64_tr_b16 v[200:201], v159 offset:37888
	ds_read_b64_tr_b16 v[202:203], v159 offset:38400
	v_exp_f32_e32 v52, v52
	v_exp_f32_e32 v53, v53
	v_add_f32_e32 v157, v157, v52
	v_add_f32_e32 v157, v157, v53
	v_cvt_pk_bf16_f32 v51, v52, v53
	s_waitcnt lgkmcnt(13)
	v_mfma_f32_32x32x16_bf16 v[238:253], v[204:207], v[82:85], v[238:253]
	ds_read_b64_tr_b16 v[204:205], v159 offset:38912
	ds_read_b64_tr_b16 v[206:207], v159 offset:39424
	v_exp_f32_e32 v54, v54
	v_exp_f32_e32 v55, v55
	v_add_f32_e32 v156, v156, v54
	v_add_f32_e32 v156, v156, v55
	v_cvt_pk_bf16_f32 v52, v54, v55
	s_waitcnt lgkmcnt(14)
	v_mfma_f32_32x32x16_bf16 v[180:195], v[208:211], v[82:85], v[180:195]
	ds_read_b64_tr_b16 v[208:209], v159 offset:39936
	ds_read_b64_tr_b16 v[210:211], v159 offset:40448
	v_exp_f32_e32 v56, v56
	v_exp_f32_e32 v57, v57
	v_add_f32_e32 v157, v157, v56
	v_add_f32_e32 v157, v157, v57
	v_cvt_pk_bf16_f32 v53, v56, v57
	s_waitcnt lgkmcnt(15)
	v_mfma_f32_32x32x16_bf16 v[238:253], v[212:215], v[78:81], v[238:253]
	ds_read_b64_tr_b16 v[212:213], v159 offset:40960
	ds_read_b64_tr_b16 v[214:215], v159 offset:41472
	v_exp_f32_e32 v58, v58
	v_exp_f32_e32 v59, v59
	v_add_f32_e32 v156, v156, v58
	v_add_f32_e32 v156, v156, v59
	v_cvt_pk_bf16_f32 v54, v58, v59
	s_waitcnt lgkmcnt(15)
	v_mfma_f32_32x32x16_bf16 v[180:195], v[230:233], v[78:81], v[180:195]
	ds_read_b64_tr_b16 v[230:231], v159 offset:41984
	ds_read_b64_tr_b16 v[232:233], v159 offset:42496
	v_exp_f32_e32 v60, v60
	v_exp_f32_e32 v61, v61
	v_add_f32_e32 v157, v157, v60
	v_add_f32_e32 v157, v157, v61
	v_cvt_pk_bf16_f32 v55, v60, v61
	s_waitcnt lgkmcnt(15)
	v_mfma_f32_32x32x16_bf16 v[238:253], v[234:237], v[74:77], v[238:253]
	ds_read_b64_tr_b16 v[234:235], v159 offset:43008
	ds_read_b64_tr_b16 v[236:237], v159 offset:43520
	v_exp_f32_e32 v62, v62
	v_exp_f32_e32 v63, v63
	v_add_f32_e32 v156, v156, v62
	v_add_f32_e32 v156, v156, v63
	v_cvt_pk_bf16_f32 v56, v62, v63
	s_waitcnt lgkmcnt(15)
	v_mfma_f32_32x32x16_bf16 v[180:195], v[164:167], v[74:77], v[180:195]
	ds_read_b64_tr_b16 v[164:165], v159 offset:44032
	ds_read_b64_tr_b16 v[166:167], v159 offset:44544
	v_exp_f32_e32 v64, v64
	v_exp_f32_e32 v65, v65
	v_add_f32_e32 v157, v157, v64
	v_add_f32_e32 v157, v157, v65
	v_cvt_pk_bf16_f32 v57, v64, v65
	s_waitcnt lgkmcnt(15)
	v_mfma_f32_32x32x16_bf16 v[238:253], v[168:171], v[70:73], v[238:253]
	v_exp_f32_e32 v34, v34
	v_exp_f32_e32 v35, v35
	v_add_f32_e32 v156, v156, v34
	v_add_f32_e32 v156, v156, v35
	v_cvt_pk_bf16_f32 v34, v34, v35
	s_waitcnt lgkmcnt(15)
	v_mfma_f32_32x32x16_bf16 v[180:195], v[172:175], v[70:73], v[180:195]
	v_exp_f32_e32 v36, v36
	v_exp_f32_e32 v37, v37
	v_add_f32_e32 v157, v157, v36
	v_add_f32_e32 v157, v157, v37
	v_cvt_pk_bf16_f32 v35, v36, v37
	s_waitcnt lgkmcnt(15)
	v_mfma_f32_32x32x16_bf16 v[238:253], v[148:151], v[66:69], v[238:253]
	v_exp_f32_e32 v38, v38
	v_exp_f32_e32 v39, v39
	v_add_f32_e32 v156, v156, v38
	v_add_f32_e32 v156, v156, v39
	v_cvt_pk_bf16_f32 v36, v38, v39
	s_waitcnt lgkmcnt(15)
	v_mfma_f32_32x32x16_bf16 v[180:195], v[152:155], v[66:69], v[180:195]
	v_exp_f32_e32 v40, v40
	v_exp_f32_e32 v41, v41
	v_add_f32_e32 v157, v157, v40
	v_add_f32_e32 v157, v157, v41
	v_cvt_pk_bf16_f32 v37, v40, v41
	s_nop 1
	s_waitcnt lgkmcnt(0)
	v_mfma_f32_32x32x16_bf16 v[18:33], v[196:199], v[50:53], v[18:33]
	v_exp_f32_e32 v42, v42
	v_exp_f32_e32 v43, v43
	v_add_f32_e32 v156, v156, v42
	v_add_f32_e32 v156, v156, v43
	v_cvt_pk_bf16_f32 v38, v42, v43
	s_nop 1
	v_mfma_f32_32x32x16_bf16 v[2:17], v[212:215], v[50:53], v[2:17]
	s_mul_i32 s63, s61, 0x3000
	s_add_i32 s4, s62, 2
	s_cmp_ge_u32 s4, s90
	s_cbranch_scc1 .Lat_u2x_nodma
	s_add_i32 s4, s63, 0xffffd000
	s_cmp_lg_u32 s61, 0
	s_cselect_b32 s4, s4, 0x6000
	s_add_i32 s5, s4, s58
	s_mov_b32 m0, s5
	s_add_i32 s4, s4, s59
	global_load_lds_dwordx4 v[126:127], off
	s_mov_b32 m0, s4
	s_cmp_lt_u32 s56, 4
	s_cbranch_scc0 .Lat_u2x_nok2
	global_load_lds_dwordx4 v[122:123], off

; #define SBAR() __builtin_amdgcn_sched_barrier(0)
; #define WAIT_BAR(N) asm volatile("s_waitcnt vmcnt(" #N ") lgkmcnt(0)\n\ts_barrier" ::: "memory")
; #define DMA_TILE(t, ks, vs) do { glds16(ksrc + (long)(t) * KVBLK * KNP, (unsigned)__builtin_amdgcn_readfirstlane(kdst + (ks) * KSLOT)); \
;         glds16(k2src + (long)(t) * KVBLK * KPP, (unsigned)__builtin_amdgcn_readfirstlane(k2dst + (ks) * KSLOT)); \
;         glds16(vsrc + (long)(t) * KVBLK * VP, (unsigned)__builtin_amdgcn_readfirstlane(vdst + (vs) * VSLOT)); } while (0)
; #define K_LOAD(ks) do { const LAS char* kp_ = kp0 + (ks) * KSLOT; \
;         _Pragma("unroll") for (int i_ = 0; i_ < 6; ++i_) { kf[2 * i_] = *(const LAS bf16x8*)(kp_ + i_ * 2048); kf[2 * i_ + 1] = *(const LAS bf16x8*)(kp_ + i_ * 2048 + 512); } SBAR(); } while (0)
; #define V_LOAD(vs) do { const LAS char* vp_ = vp0 + (vs) * VSLOT; \
;         _Pragma("unroll") for (int i_ = 0; i_ < 8; ++i_) { vlo[i_] = vtr(vp_ + ((i_ >> 2) * 4096 + (i_ & 3) * 1024)); vhi[i_] = vtr(vp_ + ((i_ >> 2) * 4096 + (i_ & 3) * 1024 + 512)); } SBAR(); } while (0)
; __device__ __forceinline__ void attn_unit(int b, int h, int qb, const bf16* Q, const bf16* __restrict__ Kn, const bf16* __restrict__ Kpe, const bf16* __restrict__ V, bf16* O, float* ASS, LAS char* shm) {
;     ...
;         for (int t = 0; t < NT; ++t) {
;             if (t + 1 < NT) { WAIT_BAR(3); } else { WAIT_BAR(0); }
;             if (t > 0) V_LOAD((vs + 3) & 3);
;             if (t + 2 < NT) DMA_TILE(t + 2, (ks == 0) ? 2 : ks - 1, (vs + 2) & 3);
;             SBAR();
;             if (t > 0) SOFTMAX();
;             K_LOAD(ks);
;             if (t > 0) PV_MMA();
;             QK_MMA(t);
;             ks = (ks == 2) ? 0 : ks + 1; vs = (vs + 1) & 3;
;         }
.Lat_u2x_end:
	s_cmp_eq_u32 s62, s90
	s_cbranch_scc1 .Lat_u2_tail
	s_waitcnt vmcnt(0) lgkmcnt(0)
	s_barrier
	s_lshr_b32 s4, s56, 1
	s_sub_u32 s4, s62, s4
	s_cmp_gt_i32 s4, s91
	s_cbranch_scc1 .Lat_u2y_noqk
	s_mul_i32 s63, s61, 0x3000
	v_add_u32_e32 v158, s63, v146
	ds_read_b128 v[196:199], v158
	ds_read_b128 v[200:203], v158 offset:512
	ds_read_b128 v[204:207], v158 offset:2048
	ds_read_b128 v[208:211], v158 offset:2560
	ds_read_b128 v[212:215], v158 offset:4096
	ds_read_b128 v[230:233], v158 offset:4608
	ds_read_b128 v[234:237], v158 offset:6144
	ds_read_b128 v[164:167], v158 offset:6656
	ds_read_b128 v[168:171], v158 offset:8192
	ds_read_b128 v[172:175], v158 offset:8704
	ds_read_b128 v[148:151], v158 offset:10240
	ds_read_b128 v[152:155], v158 offset:10752
	s_lshl_b32 s4, s64, 13
	s_add_i32 s4, s4, 0x6000
	s_and_b32 s4, s4, 0x6000
	v_add_u32_e32 v159, s4, v143
	v_mov_b32_e32 v156, 0
	v_mov_b32_e32 v157, 0
	s_waitcnt lgkmcnt(11)
	v_mfma_f32_32x32x16_bf16 v[50:65], v[196:199], v[86:89], v[104:119]
	ds_read_b64_tr_b16 v[196:197], v159 offset:36864
	ds_read_b64_tr_b16 v[198:199], v159 offset:37376
	v_exp_f32_e32 v238, v238
	v_exp_f32_e32 v239, v239
	v_add_f32_e32 v156, v156, v238
	v_add_f32_e32 v156, v156, v239
	v_cvt_pk_bf16_f32 v238, v238, v239
	s_waitcnt lgkmcnt(12)
	v_mfma_f32_32x32x16_bf16 v[34:49], v[200:203], v[86:89], v[104:119]
	ds_read_b64_tr_b16 v[200:201], v159 offset:37888
	ds_read_b64_tr_b16 v[202:203], v159 offset:38400
	v_exp_f32_e32 v240, v240
	v_exp_f32_e32 v241, v241
	v_add_f32_e32 v157, v157, v240
	v_add_f32_e32 v157, v157, v241
	v_cvt_pk_bf16_f32 v239, v240, v241
	s_waitcnt lgkmcnt(13)
	v_mfma_f32_32x32x16_bf16 v[50:65], v[204:207], v[82:85], v[50:65]
	ds_read_b64_tr_b16 v[204:205], v159 offset:38912
	ds_read_b64_tr_b16 v[206:207], v159 offset:39424
	v_exp_f32_e32 v242, v242
	v_exp_f32_e32 v243, v243
	v_add_f32_e32 v156, v156, v242
	v_add_f32_e32 v156, v156, v243
	v_cvt_pk_bf16_f32 v240, v242, v243
	s_waitcnt lgkmcnt(14)
	v_mfma_f32_32x32x16_bf16 v[34:49], v[208:211], v[82:85], v[34:49]
	ds_read_b64_tr_b16 v[208:209], v159 offset:39936
	ds_read_b64_tr_b16 v[210:211], v159 offset:40448
	v_exp_f32_e32 v244, v244
	v_exp_f32_e32 v245, v245
	v_add_f32_e32 v157, v157, v244
	v_add_f32_e32 v157, v157, v245
	v_cvt_pk_bf16_f32 v241, v244, v245
	s_waitcnt lgkmcnt(15)
	v_mfma_f32_32x32x16_bf16 v[50:65], v[212:215], v[78:81], v[50:65]
	ds_read_b64_tr_b16 v[212:213], v159 offset:40960
	ds_read_b64_tr_b16 v[214:215], v159 offset:41472
	v_exp_f32_e32 v246, v246
	v_exp_f32_e32 v247, v247
	v_add_f32_e32 v156, v156, v246
	v_add_f32_e32 v156, v156, v247
	v_cvt_pk_bf16_f32 v242, v246, v247
	s_waitcnt lgkmcnt(15)
	v_mfma_f32_32x32x16_bf16 v[34:49], v[230:233], v[78:81], v[34:49]
	ds_read_b64_tr_b16 v[230:231], v159 offset:41984
	ds_read_b64_tr_b16 v[232:233], v159 offset:42496
	v_exp_f32_e32 v248, v248
	v_exp_f32_e32 v249, v249
	v_add_f32_e32 v157, v157, v248
	v_add_f32_e32 v157, v157, v249
	v_cvt_pk_bf16_f32 v243, v248, v249
	s_waitcnt lgkmcnt(15)
	v_mfma_f32_32x32x16_bf16 v[50:65], v[234:237], v[74:77], v[50:65]
	ds_read_b64_tr_b16 v[234:235], v159 offset:43008
	ds_read_b64_tr_b16 v[236:237], v159 offset:43520
	v_exp_f32_e32 v250, v250
	v_exp_f32_e32 v251, v251
	v_add_f32_e32 v156, v156, v250
	v_add_f32_e32 v156, v156, v251
	v_cvt_pk_bf16_f32 v244, v250, v251
	s_waitcnt lgkmcnt(15)
	v_mfma_f32_32x32x16_bf16 v[34:49], v[164:167], v[74:77], v[34:49]
	ds_read_b64_tr_b16 v[164:165], v159 offset:44032
	ds_read_b64_tr_b16 v[166:167], v159 offset:44544
	v_exp_f32_e32 v252, v252
	v_exp_f32_e32 v253, v253
	v_add_f32_e32 v157, v157, v252
	v_add_f32_e32 v157, v157, v253
	v_cvt_pk_bf16_f32 v245, v252, v253
	s_waitcnt lgkmcnt(15)
	v_mfma_f32_32x32x16_bf16 v[50:65], v[168:171], v[70:73], v[50:65]
	v_exp_f32_e32 v180, v180
	v_exp_f32_e32 v181, v181
	v_add_f32_e32 v156, v156, v180
	v_add_f32_e32 v156, v156, v181
	v_cvt_pk_bf16_f32 v180, v180, v181
	s_waitcnt lgkmcnt(15)
	v_mfma_f32_32x32x16_bf16 v[34:49], v[172:175], v[70:73], v[34:49]
	v_exp_f32_e32 v182, v182
	v_exp_f32_e32 v183, v183
	v_add_f32_e32 v157, v157, v182
	v_add_f32_e32 v157, v157, v183
	v_cvt_pk_bf16_f32 v181, v182, v183
	s_waitcnt lgkmcnt(15)
	v_mfma_f32_32x32x16_bf16 v[50:65], v[148:151], v[66:69], v[50:65]
	v_exp_f32_e32 v184, v184
	v_exp_f32_e32 v185, v185
	v_add_f32_e32 v156, v156, v184
	v_add_f32_e32 v156, v156, v185
	v_cvt_pk_bf16_f32 v182, v184, v185
	s_waitcnt lgkmcnt(15)
	v_mfma_f32_32x32x16_bf16 v[34:49], v[152:155], v[66:69], v[34:49]
	v_exp_f32_e32 v186, v186
	v_exp_f32_e32 v187, v187
	v_add_f32_e32 v157, v157, v186
	v_add_f32_e32 v157, v157, v187
	v_cvt_pk_bf16_f32 v183, v186, v187
	s_nop 1
	s_waitcnt lgkmcnt(0)
	v_mfma_f32_32x32x16_bf16 v[18:33], v[196:199], v[238:241], v[18:33]
	v_exp_f32_e32 v188, v188
	v_exp_f32_e32 v189, v189
	v_add_f32_e32 v156, v156, v188
	v_add_f32_e32 v156, v156, v189
	v_cvt_pk_bf16_f32 v184, v188, v189
	s_nop 1
	v_mfma_f32_32x32x16_bf16 v[2:17], v[212:215], v[238:241], v[2:17]
	s_mul_i32 s63, s61, 0x3000
	s_add_i32 s4, s62, 2
	s_cmp_ge_u32 s4, s90
	s_cbranch_scc1 .Lat_u2y_nodma
	s_add_i32 s4, s63, 0xffffd000
	s_cmp_lg_u32 s61, 0
	s_cselect_b32 s4, s4, 0x6000
	s_add_i32 s5, s4, s58
	s_mov_b32 m0, s5
	s_add_i32 s4, s4, s59
	global_load_lds_dwordx4 v[126:127], off
	s_mov_b32 m0, s4
	s_cmp_lt_u32 s56, 4
	s_cbranch_scc0 .Lat_u2y_nok2
	global_load_lds_dwordx4 v[122:123], off
